# diff attention loop: rare rescale blocks moved out of line (common path falls through)
# speedup vs baseline: 1.0007x; 1.0007x over previous
.LBB0_583:
	s_andn2_b64 vcc, exec, s[2:3]
	s_andn2_b64 s[2:3], exec, s[0:1]
	s_cbranch_vccz .Ldiff_rare_a1

.LBB0_590:
	s_andn2_b64 vcc, exec, s[0:1]
	s_cbranch_vccz .Ldiff_rare_a2
.LBB0_594:
.LBB0_595:
	v_pk_add_f32 v[192:193], v[224:225], v[226:227]
	v_pk_add_f32 v[194:195], v[228:229], v[230:231]
	v_pk_add_f32 v[198:199], v[232:233], v[234:235]
	v_add_f32_e32 v200, v223, v238
	v_exp_f32_e32 v128, v128
	v_exp_f32_e32 v129, v129
	v_exp_f32_e32 v130, v130
	v_exp_f32_e32 v131, v131
	v_pk_add_f32 v[192:193], v[192:193], v[194:195]
	v_pk_add_f32 v[198:199], v[198:199], v[236:237]
	v_exp_f32_e32 v132, v132
	v_exp_f32_e32 v133, v133
	v_exp_f32_e32 v134, v134
	v_exp_f32_e32 v135, v135
	v_pk_add_f32 v[192:193], v[192:193], v[198:199]
	v_add_f32_e32 v200, v200, v192
	v_add_f32_e32 v200, v200, v193
	v_add_f32_e32 v220, v220, v200
	v_cvt_pk_bf16_f32 v192, v128, v129
	v_cvt_pk_bf16_f32 v193, v130, v131
	v_cvt_pk_bf16_f32 v194, v132, v133
	v_cvt_pk_bf16_f32 v195, v134, v135
	v_exp_f32_e32 v136, v136
	v_exp_f32_e32 v137, v137
	v_mfma_f32_32x32x16_bf16 v[48:63], v[168:171], v[192:195], v[48:63]
	ds_read_b128 v[168:171], v222 offset:4096
	v_exp_f32_e32 v138, v138
	v_exp_f32_e32 v139, v139
	v_exp_f32_e32 v140, v140
	v_exp_f32_e32 v141, v141
	v_exp_f32_e32 v142, v142
	v_exp_f32_e32 v143, v143
	s_waitcnt lgkmcnt(0)
	v_mfma_f32_32x32x16_bf16 v[96:111], v[168:171], v[148:151], v[80:95]
	ds_read_b128 v[168:171], v221 offset:4096
	v_cvt_pk_bf16_f32 v198, v136, v137
	v_cvt_pk_bf16_f32 v199, v138, v139
	v_cvt_pk_bf16_f32 v200, v140, v141
	v_cvt_pk_bf16_f32 v201, v142, v143
	v_mfma_f32_32x32x16_bf16 v[16:31], v[160:163], v[192:195], v[16:31]
	s_waitcnt lgkmcnt(0)
	v_mfma_f32_32x32x16_bf16 v[96:111], v[168:171], v[156:159], v[96:111]
	v_max3_f32 v168, v112, v113, v114
	v_max_f32_e32 v168, v168, v115
	v_max3_f32 v168, v168, v116, v117
	v_max3_f32 v168, v168, v118, v119
	v_max3_f32 v168, v168, v120, v121
	v_mfma_f32_32x32x16_bf16 v[48:63], v[172:175], v[198:201], v[48:63]
	v_max3_f32 v168, v168, v122, v123
	v_max3_f32 v168, v168, v124, v125
	v_max3_f32 v168, v168, v126, v127
	v_cmp_ge_f32_e32 vcc, s85, v168
	s_cmp_eq_u64 vcc, exec
	v_mfma_f32_32x32x16_bf16 v[16:31], v[164:167], v[198:201], v[16:31]
	s_cbranch_scc0 .Ldiff_rare_b1

.Ldiff_rare_a1:
	v_and_b32_e32 v65, 64, v196
	v_xor_b32_e32 v64, 32, v196
	v_add_u32_e32 v65, 64, v65
	v_cmp_lt_i32_e32 vcc, v64, v65
	v_max_f32_e32 v65, v112, v112
	s_nop 0
	v_cndmask_b32_e32 v64, v196, v64, vcc
	v_lshlrev_b32_e32 v64, 2, v64
	ds_bpermute_b32 v64, v64, v112
	s_and_b64 vcc, exec, s[2:3]
	s_waitcnt lgkmcnt(0)
	v_max_f32_e32 v64, v64, v64
	v_max_f32_e32 v64, v65, v64
	v_max_f32_e32 v65, 0, v64
	s_cbranch_vccnz .LBB0_586
	v_exp_f32_e64 v66, -v65
	s_nop 0
	v_mul_f32_e32 v220, v220, v66
	v_pk_mul_f32 v[14:15], v[14:15], v[66:67] op_sel_hi:[1,0]
	v_pk_mul_f32 v[12:13], v[12:13], v[66:67] op_sel_hi:[1,0]
	v_pk_mul_f32 v[10:11], v[10:11], v[66:67] op_sel_hi:[1,0]
	v_pk_mul_f32 v[8:9], v[8:9], v[66:67] op_sel_hi:[1,0]
	v_pk_mul_f32 v[6:7], v[6:7], v[66:67] op_sel_hi:[1,0]
	v_pk_mul_f32 v[4:5], v[4:5], v[66:67] op_sel_hi:[1,0]
	v_pk_mul_f32 v[2:3], v[2:3], v[66:67] op_sel_hi:[1,0]
	v_pk_mul_f32 v[0:1], v[0:1], v[66:67] op_sel_hi:[1,0]
	v_pk_mul_f32 v[46:47], v[46:47], v[66:67] op_sel_hi:[1,0]
	v_pk_mul_f32 v[44:45], v[44:45], v[66:67] op_sel_hi:[1,0]
	v_pk_mul_f32 v[42:43], v[42:43], v[66:67] op_sel_hi:[1,0]
	v_pk_mul_f32 v[40:41], v[40:41], v[66:67] op_sel_hi:[1,0]
	v_pk_mul_f32 v[38:39], v[38:39], v[66:67] op_sel_hi:[1,0]
	v_pk_mul_f32 v[36:37], v[36:37], v[66:67] op_sel_hi:[1,0]
	v_pk_mul_f32 v[34:35], v[34:35], v[66:67] op_sel_hi:[1,0]
	v_pk_mul_f32 v[32:33], v[32:33], v[66:67] op_sel_hi:[1,0]

.Ldiff_rare_a2:
	v_and_b32_e32 v81, 64, v196
	v_xor_b32_e32 v80, 32, v196
	v_add_u32_e32 v81, 64, v81
	v_cmp_lt_i32_e32 vcc, v80, v81
	v_max_f32_e32 v81, v96, v96
	s_nop 0
	v_cndmask_b32_e32 v80, v196, v80, vcc
	v_lshlrev_b32_e32 v80, 2, v80
	ds_bpermute_b32 v80, v80, v96
	s_and_b64 vcc, exec, s[2:3]
	s_waitcnt lgkmcnt(0)
	v_max_f32_e32 v80, v80, v80
	v_max_f32_e32 v80, v81, v80
	v_max_f32_e32 v81, 0, v80
	s_cbranch_vccnz .LBB0_593
	v_exp_f32_e64 v82, -v81
	s_nop 0
	v_mul_f32_e32 v219, v219, v82
	v_pk_mul_f32 v[62:63], v[62:63], v[82:83] op_sel_hi:[1,0]
	v_pk_mul_f32 v[60:61], v[60:61], v[82:83] op_sel_hi:[1,0]
	v_pk_mul_f32 v[58:59], v[58:59], v[82:83] op_sel_hi:[1,0]
	v_pk_mul_f32 v[56:57], v[56:57], v[82:83] op_sel_hi:[1,0]
	v_pk_mul_f32 v[54:55], v[54:55], v[82:83] op_sel_hi:[1,0]
	v_pk_mul_f32 v[52:53], v[52:53], v[82:83] op_sel_hi:[1,0]
	v_pk_mul_f32 v[50:51], v[50:51], v[82:83] op_sel_hi:[1,0]
	v_pk_mul_f32 v[48:49], v[48:49], v[82:83] op_sel_hi:[1,0]
	v_pk_mul_f32 v[30:31], v[30:31], v[82:83] op_sel_hi:[1,0]
	v_pk_mul_f32 v[28:29], v[28:29], v[82:83] op_sel_hi:[1,0]
	v_pk_mul_f32 v[26:27], v[26:27], v[82:83] op_sel_hi:[1,0]
	v_pk_mul_f32 v[24:25], v[24:25], v[82:83] op_sel_hi:[1,0]
	v_pk_mul_f32 v[22:23], v[22:23], v[82:83] op_sel_hi:[1,0]
	v_pk_mul_f32 v[20:21], v[20:21], v[82:83] op_sel_hi:[1,0]
	v_pk_mul_f32 v[18:19], v[18:19], v[82:83] op_sel_hi:[1,0]
	v_pk_mul_f32 v[16:17], v[16:17], v[82:83] op_sel_hi:[1,0]

.Ldiff_rare_b1:
	v_and_b32_e32 v65, 64, v196
	v_xor_b32_e32 v64, 32, v196
	v_add_u32_e32 v65, 64, v65
	v_cmp_lt_i32_e32 vcc, v64, v65
	s_nop 1
	v_cndmask_b32_e32 v64, v196, v64, vcc
	v_lshlrev_b32_e32 v64, 2, v64
	ds_bpermute_b32 v64, v64, v168
	s_waitcnt lgkmcnt(0)
	v_max3_f32 v66, v168, v64, 0
	v_exp_f32_e64 v68, -v66
	v_add_f32_e32 v213, v213, v66
	v_xor_b32_e32 v64, 0x80000000, v213
	v_pk_add_f32 v[112:113], v[112:113], v[66:67] op_sel_hi:[1,0] neg_lo:[0,1] neg_hi:[0,1]
	v_pk_mul_f32 v[46:47], v[46:47], v[68:69] op_sel_hi:[1,0]
	v_pk_mul_f32 v[44:45], v[44:45], v[68:69] op_sel_hi:[1,0]
	v_pk_mul_f32 v[42:43], v[42:43], v[68:69] op_sel_hi:[1,0]
	v_pk_mul_f32 v[40:41], v[40:41], v[68:69] op_sel_hi:[1,0]
	v_pk_mul_f32 v[38:39], v[38:39], v[68:69] op_sel_hi:[1,0]
	v_pk_mul_f32 v[36:37], v[36:37], v[68:69] op_sel_hi:[1,0]
	v_pk_mul_f32 v[34:35], v[34:35], v[68:69] op_sel_hi:[1,0]
	v_pk_mul_f32 v[32:33], v[32:33], v[68:69] op_sel_hi:[1,0]
	v_pk_add_f32 v[114:115], v[114:115], v[66:67] op_sel_hi:[1,0] neg_lo:[0,1] neg_hi:[0,1]
	v_pk_add_f32 v[116:117], v[116:117], v[66:67] op_sel_hi:[1,0] neg_lo:[0,1] neg_hi:[0,1]
	v_pk_add_f32 v[118:119], v[118:119], v[66:67] op_sel_hi:[1,0] neg_lo:[0,1] neg_hi:[0,1]
	v_pk_add_f32 v[120:121], v[120:121], v[66:67] op_sel_hi:[1,0] neg_lo:[0,1] neg_hi:[0,1]
	v_pk_add_f32 v[122:123], v[122:123], v[66:67] op_sel_hi:[1,0] neg_lo:[0,1] neg_hi:[0,1]
	v_pk_add_f32 v[124:125], v[124:125], v[66:67] op_sel_hi:[1,0] neg_lo:[0,1] neg_hi:[0,1]
	v_pk_add_f32 v[126:127], v[126:127], v[66:67] op_sel_hi:[1,0] neg_lo:[0,1] neg_hi:[0,1]
	v_mul_f32_e32 v220, v220, v68
	v_pk_mul_f32 v[14:15], v[14:15], v[68:69] op_sel_hi:[1,0]
	v_pk_mul_f32 v[12:13], v[12:13], v[68:69] op_sel_hi:[1,0]
	v_pk_mul_f32 v[10:11], v[10:11], v[68:69] op_sel_hi:[1,0]
	v_pk_mul_f32 v[8:9], v[8:9], v[68:69] op_sel_hi:[1,0]
	v_pk_mul_f32 v[6:7], v[6:7], v[68:69] op_sel_hi:[1,0]
	v_pk_mul_f32 v[4:5], v[4:5], v[68:69] op_sel_hi:[1,0]
	v_pk_mul_f32 v[2:3], v[2:3], v[68:69] op_sel_hi:[1,0]
	v_pk_mul_f32 v[0:1], v[0:1], v[68:69] op_sel_hi:[1,0]
	v_mov_b32_e32 v65, v64
	v_mov_b32_e32 v66, v64
	v_mov_b32_e32 v67, v64
	v_mov_b32_e32 v68, v64
	v_mov_b32_e32 v69, v64
	v_mov_b32_e32 v70, v64
	v_mov_b32_e32 v71, v64
	v_mov_b32_e32 v72, v64
	v_mov_b32_e32 v73, v64
	v_mov_b32_e32 v74, v64
	v_mov_b32_e32 v75, v64
	v_mov_b32_e32 v76, v64
	v_mov_b32_e32 v77, v64
	v_mov_b32_e32 v78, v64
	v_mov_b32_e32 v79, v64
	s_branch .LBB0_597
